# up-proj MFMA main loop: one static priority raise for the wave half that enters second instead of per-segment s_setprio toggles
# speedup vs baseline: 1.0063x; 1.0014x over previous
.LBB0_1300:
	s_andn2_b64 vcc, exec, s[4:5]
	s_cbranch_vccnz .LBB0_1471
	v_lshlrev_b32_e32 v158, 4, v156
	s_waitcnt vmcnt(0)
	v_and_b32_e32 v0, 32, v156
	s_add_u32 s9, s40, 0x2100000
	v_bfe_u32 v8, v156, 2, 4
	v_bitop3_b32 v6, v158, v0, 48 bitop3:0x6c
	v_and_b32_e32 v7, 64, v156
	v_lshrrev_b32_e32 v1, 3, v156
	s_movk_i32 s5, 0x70
	s_addc_u32 s12, s41, 0
	v_or_b32_e32 v0, v6, v7
	v_and_or_b32 v1, v1, s5, v8
	v_add_u32_e32 v9, 0x2000, v158
	s_add_u32 s13, s40, 0xe534f00
	v_lshl_or_b32 v160, v1, 12, v0
	v_lshrrev_b32_e32 v1, 7, v9
	s_movk_i32 s5, 0xf0
	s_addc_u32 s14, s41, 0
	v_and_or_b32 v1, v1, s5, v8
	s_lshr_b32 s5, s11, 6
	s_ashr_i32 s17, s16, 31
	s_lshl_b32 s8, s10, 20
	s_lshr_b32 s4, s11, 8
	s_lshl_b32 s96, s5, 10
	s_lshl_b64 s[6:7], s[16:17], 20
	s_and_b32 s8, s8, 0xff00000
	s_add_u32 s18, s9, s8
	s_addc_u32 s19, s12, 0
	s_add_i32 s97, s96, 0
	v_mov_b32_e32 v165, 0
	s_add_i32 m0, s97, 0x10000
	v_mov_b32_e32 v159, v165
	v_lshl_or_b32 v162, v1, 12, v0
	v_lshl_add_u64 v[0:1], s[18:19], 0, v[158:159]
	global_load_lds_dwordx4 v158, s[18:19]
	s_mov_b64 s[28:29], 0x2000
	s_add_i32 m0, s97, 0x12000
	v_lshl_add_u64 v[2:3], v[0:1], 0, s[28:29]
	s_add_u32 s20, s13, s6
	global_load_lds_dwordx4 v[2:3], off
	s_addc_u32 s21, s14, s7
	s_mov_b32 m0, s97
	s_add_i32 s33, s97, 0x2000
	global_load_lds_dwordx4 v160, s[20:21]
	s_mov_b32 m0, s33
	s_mov_b64 s[30:31], 0x80000
	global_load_lds_dwordx4 v162, s[20:21]
	s_add_i32 m0, s97, 0x14000
	v_lshl_add_u64 v[2:3], v[0:1], 0, s[30:31]
	global_load_lds_dwordx4 v[2:3], off
	s_add_i32 m0, s97, 0x16000
	s_mov_b64 s[34:35], 0x82000
	s_add_u32 s6, s20, 0x80000
	v_lshl_add_u64 v[2:3], v[0:1], 0, s[34:35]
	s_addc_u32 s7, s21, 0
	s_add_i32 s22, s97, 0x4000
	global_load_lds_dwordx4 v[2:3], off
	s_mov_b32 m0, s22
	s_add_i32 s23, s97, 0x6000
	global_load_lds_dwordx4 v160, s[6:7]
	s_mov_b32 m0, s23
	v_writelane_b32 v243, s66, 3
	global_load_lds_dwordx4 v162, s[6:7]
	s_nop 0
	v_writelane_b32 v243, s67, 4
	v_writelane_b32 v243, s11, 5
	v_writelane_b32 v243, s9, 0
	v_writelane_b32 v243, s12, 2
	v_writelane_b32 v243, s13, 6
	v_writelane_b32 v243, s14, 7
	s_load_dwordx2 s[14:15], s[0:1], 0x90
	s_load_dwordx4 s[24:27], s[0:1], 0x70
	v_mov_b32_e32 v161, v165
	v_mov_b32_e32 v163, v165
	v_lshrrev_b32_e32 v10, 2, v156
	s_mov_b32 s39, 0
	v_lshl_add_u64 v[4:5], s[20:21], 0, v[160:161]
	v_lshl_add_u64 v[2:3], s[20:21], 0, v[162:163]
	s_cmp_lg_u32 s4, 1
	s_cbranch_scc1 .LBB0_1303
	s_barrier
	s_setprio 1

.LBB0_1313:
	ds_read_b128 v[128:131], v215
	ds_read_b128 v[132:135], v215 offset:1024
	ds_read_b128 v[136:139], v215 offset:2048
	ds_read_b128 v[140:143], v215 offset:3072
	s_add_u32 s20, s18, 0xfff80080
	s_addc_u32 s21, s19, -1
	s_cmp_eq_u32 s86, 28
	s_cselect_b32 s21, s11, s21
	s_cselect_b32 s20, s17, s20
	s_cselect_b32 s89, s38, s85
	s_cselect_b32 s88, s79, s84
	v_lshl_add_u64 v[200:201], s[18:19], 0, v[168:169]
	s_add_i32 m0, s97, 0xc000
	ds_read_b128 v[144:147], v216
	ds_read_b128 v[148:151], v216 offset:1024
	ds_read_b128 v[152:155], v216 offset:2048
	ds_read_b128 v[178:181], v216 offset:3072
	ds_read_b128 v[182:185], v216 offset:4096
	ds_read_b128 v[186:189], v216 offset:5120
	ds_read_b128 v[192:195], v216 offset:6144
	ds_read_b128 v[196:199], v216 offset:7168
	global_load_lds_dwordx4 v[200:201], off
	v_lshl_add_u64 v[200:201], s[18:19], 0, v[170:171]
	s_add_i32 m0, s97, 0xe000
	s_nop 0
	global_load_lds_dwordx4 v[200:201], off
	s_waitcnt lgkmcnt(8)
	s_barrier
	s_waitcnt lgkmcnt(0)
	s_waitcnt lgkmcnt(0)
	v_mfma_f32_16x16x32_bf16 v[124:127], v[128:131], v[144:147], v[124:127]
	v_mfma_f32_16x16x32_bf16 v[92:95], v[136:139], v[144:147], v[92:95]
	v_mfma_f32_16x16x32_bf16 v[120:123], v[128:131], v[152:155], v[120:123]
	v_mfma_f32_16x16x32_bf16 v[88:91], v[136:139], v[152:155], v[88:91]
	v_mfma_f32_16x16x32_bf16 v[116:119], v[128:131], v[182:185], v[116:119]
	v_mfma_f32_16x16x32_bf16 v[84:87], v[136:139], v[182:185], v[84:87]
	v_mfma_f32_16x16x32_bf16 v[112:115], v[128:131], v[192:195], v[112:115]
	v_mfma_f32_16x16x32_bf16 v[80:83], v[136:139], v[192:195], v[80:83]
	v_mfma_f32_16x16x32_bf16 v[124:127], v[132:135], v[148:151], v[124:127]
	v_mfma_f32_16x16x32_bf16 v[92:95], v[140:143], v[148:151], v[92:95]
	v_mfma_f32_16x16x32_bf16 v[120:123], v[132:135], v[178:181], v[120:123]
	v_mfma_f32_16x16x32_bf16 v[88:91], v[140:143], v[178:181], v[88:91]
	v_mfma_f32_16x16x32_bf16 v[116:119], v[132:135], v[186:189], v[116:119]
	v_mfma_f32_16x16x32_bf16 v[84:87], v[140:143], v[186:189], v[84:87]
	v_mfma_f32_16x16x32_bf16 v[112:115], v[132:135], v[196:199], v[112:115]
	v_mfma_f32_16x16x32_bf16 v[80:83], v[140:143], v[196:199], v[80:83]
	s_barrier
	s_add_i32 s87, s94, s96
	v_lshl_add_u64 v[212:213], s[88:89], 0, v[158:159]
	s_mov_b32 m0, s87
	ds_read_b128 v[200:203], v217
	ds_read_b128 v[204:207], v217 offset:1024
	ds_read_b128 v[208:211], v217 offset:2048
	ds_read_b128 v[220:223], v217 offset:3072
	global_load_lds_dwordx4 v[212:213], off
	v_lshl_add_u64 v[224:225], v[212:213], 0, s[28:29]
	s_add_i32 m0, s87, 0x2000
	s_nop 0
	global_load_lds_dwordx4 v[224:225], off
	s_barrier
	s_waitcnt lgkmcnt(0)
	s_waitcnt lgkmcnt(0)
	v_mfma_f32_16x16x32_bf16 v[108:111], v[200:203], v[144:147], v[108:111]
	v_mfma_f32_16x16x32_bf16 v[76:79], v[208:211], v[144:147], v[76:79]
	v_mfma_f32_16x16x32_bf16 v[104:107], v[200:203], v[152:155], v[104:107]
	v_mfma_f32_16x16x32_bf16 v[72:75], v[208:211], v[152:155], v[72:75]
	v_mfma_f32_16x16x32_bf16 v[100:103], v[200:203], v[182:185], v[100:103]
	v_mfma_f32_16x16x32_bf16 v[68:71], v[208:211], v[182:185], v[68:71]
	v_mfma_f32_16x16x32_bf16 v[96:99], v[200:203], v[192:195], v[96:99]
	v_mfma_f32_16x16x32_bf16 v[64:67], v[208:211], v[192:195], v[64:67]
	v_mfma_f32_16x16x32_bf16 v[108:111], v[204:207], v[148:151], v[108:111]
	v_mfma_f32_16x16x32_bf16 v[76:79], v[220:223], v[148:151], v[76:79]
	v_mfma_f32_16x16x32_bf16 v[104:107], v[204:207], v[178:181], v[104:107]
	v_mfma_f32_16x16x32_bf16 v[72:75], v[220:223], v[178:181], v[72:75]
	v_mfma_f32_16x16x32_bf16 v[100:103], v[204:207], v[186:189], v[100:103]
	v_mfma_f32_16x16x32_bf16 v[68:71], v[220:223], v[186:189], v[68:71]
	v_mfma_f32_16x16x32_bf16 v[96:99], v[204:207], v[196:199], v[96:99]
	v_mfma_f32_16x16x32_bf16 v[64:67], v[220:223], v[196:199], v[64:67]
	s_mov_b32 m0, s97
	v_lshl_add_u64 v[224:225], s[20:21], 0, v[160:161]
	s_barrier
	ds_read_b128 v[144:147], v216 offset:16384
	ds_read_b128 v[148:151], v216 offset:17408
	ds_read_b128 v[152:155], v216 offset:18432
	ds_read_b128 v[178:181], v216 offset:19456
	ds_read_b128 v[182:185], v216 offset:20480
	ds_read_b128 v[186:189], v216 offset:21504
	ds_read_b128 v[192:195], v216 offset:22528
	ds_read_b128 v[196:199], v216 offset:23552
	global_load_lds_dwordx4 v[224:225], off
	v_lshl_add_u64 v[226:227], s[20:21], 0, v[162:163]
	s_mov_b32 m0, s33
	s_nop 0
	global_load_lds_dwordx4 v[226:227], off
	s_barrier
	s_waitcnt lgkmcnt(0)
	s_waitcnt lgkmcnt(0)
	v_mfma_f32_16x16x32_bf16 v[60:63], v[128:131], v[144:147], v[60:63]
	v_mfma_f32_16x16x32_bf16 v[28:31], v[136:139], v[144:147], v[28:31]
	v_mfma_f32_16x16x32_bf16 v[56:59], v[128:131], v[152:155], v[56:59]
	v_mfma_f32_16x16x32_bf16 v[24:27], v[136:139], v[152:155], v[24:27]
	v_mfma_f32_16x16x32_bf16 v[52:55], v[128:131], v[182:185], v[52:55]
	v_mfma_f32_16x16x32_bf16 v[20:23], v[136:139], v[182:185], v[20:23]
	v_mfma_f32_16x16x32_bf16 v[48:51], v[128:131], v[192:195], v[48:51]
	v_mfma_f32_16x16x32_bf16 v[16:19], v[136:139], v[192:195], v[16:19]
	v_mfma_f32_16x16x32_bf16 v[60:63], v[132:135], v[148:151], v[60:63]
	v_mfma_f32_16x16x32_bf16 v[28:31], v[140:143], v[148:151], v[28:31]
	v_mfma_f32_16x16x32_bf16 v[56:59], v[132:135], v[178:181], v[56:59]
	v_mfma_f32_16x16x32_bf16 v[24:27], v[140:143], v[178:181], v[24:27]
	v_mfma_f32_16x16x32_bf16 v[52:55], v[132:135], v[186:189], v[52:55]
	v_mfma_f32_16x16x32_bf16 v[20:23], v[140:143], v[186:189], v[20:23]
	v_mfma_f32_16x16x32_bf16 v[48:51], v[132:135], v[196:199], v[48:51]
	v_mfma_f32_16x16x32_bf16 v[16:19], v[140:143], v[196:199], v[16:19]
	s_barrier
	s_add_i32 s87, s95, s96
	v_lshl_add_u64 v[128:129], v[212:213], 0, s[30:31]
	s_mov_b32 m0, s87
	s_nop 0
	global_load_lds_dwordx4 v[128:129], off
	v_lshl_add_u64 v[128:129], v[212:213], 0, s[34:35]
	s_add_i32 m0, s87, 0x2000
	s_nop 0
	global_load_lds_dwordx4 v[128:129], off
	s_waitcnt vmcnt(6)
	s_barrier
	v_mfma_f32_16x16x32_bf16 v[44:47], v[200:203], v[144:147], v[44:47]
	v_mfma_f32_16x16x32_bf16 v[12:15], v[208:211], v[144:147], v[12:15]
	v_mfma_f32_16x16x32_bf16 v[40:43], v[200:203], v[152:155], v[40:43]
	v_mfma_f32_16x16x32_bf16 v[8:11], v[208:211], v[152:155], v[8:11]
	v_mfma_f32_16x16x32_bf16 v[36:39], v[200:203], v[182:185], v[36:39]
	v_mfma_f32_16x16x32_bf16 v[4:7], v[208:211], v[182:185], v[4:7]
	v_mfma_f32_16x16x32_bf16 v[32:35], v[200:203], v[192:195], v[32:35]
	v_mfma_f32_16x16x32_bf16 v[0:3], v[208:211], v[192:195], v[0:3]
	v_mfma_f32_16x16x32_bf16 v[44:47], v[204:207], v[148:151], v[44:47]
	v_mfma_f32_16x16x32_bf16 v[12:15], v[220:223], v[148:151], v[12:15]
	v_mfma_f32_16x16x32_bf16 v[40:43], v[204:207], v[178:181], v[40:43]
	v_mfma_f32_16x16x32_bf16 v[8:11], v[220:223], v[178:181], v[8:11]
	v_mfma_f32_16x16x32_bf16 v[36:39], v[204:207], v[186:189], v[36:39]
	v_mfma_f32_16x16x32_bf16 v[4:7], v[220:223], v[186:189], v[4:7]
	v_mfma_f32_16x16x32_bf16 v[32:35], v[204:207], v[196:199], v[32:35]
	v_mfma_f32_16x16x32_bf16 v[0:3], v[220:223], v[196:199], v[0:3]
	s_add_i32 s87, 0, 0x18000
	v_add_u32_e32 v140, s87, v167
	s_barrier
	ds_read_b128 v[128:131], v140
	ds_read_b128 v[132:135], v140 offset:1024
	ds_read_b128 v[136:139], v140 offset:2048
	ds_read_b128 v[140:143], v140 offset:3072
	s_add_u32 s20, s20, 0x80000
	s_addc_u32 s21, s21, 0
	s_mov_b32 m0, s22
	v_lshl_add_u64 v[200:201], s[20:21], 0, v[160:161]
	ds_read_b128 v[144:147], v216 offset:32768
	ds_read_b128 v[148:151], v216 offset:33792
	ds_read_b128 v[152:155], v216 offset:34816
	ds_read_b128 v[178:181], v216 offset:35840
	ds_read_b128 v[182:185], v216 offset:36864
	ds_read_b128 v[186:189], v216 offset:37888
	ds_read_b128 v[192:195], v216 offset:38912
	ds_read_b128 v[196:199], v216 offset:39936
	global_load_lds_dwordx4 v[200:201], off
	v_lshl_add_u64 v[200:201], s[20:21], 0, v[162:163]
	s_mov_b32 m0, s23
	s_nop 0
	global_load_lds_dwordx4 v[200:201], off
	s_waitcnt lgkmcnt(8)
	s_barrier
	s_waitcnt lgkmcnt(0)
	s_waitcnt lgkmcnt(0)
	v_mfma_f32_16x16x32_bf16 v[124:127], v[128:131], v[144:147], v[124:127]
	v_mfma_f32_16x16x32_bf16 v[92:95], v[136:139], v[144:147], v[92:95]
	v_mfma_f32_16x16x32_bf16 v[120:123], v[128:131], v[152:155], v[120:123]
	v_mfma_f32_16x16x32_bf16 v[88:91], v[136:139], v[152:155], v[88:91]
	v_mfma_f32_16x16x32_bf16 v[116:119], v[128:131], v[182:185], v[116:119]
	v_mfma_f32_16x16x32_bf16 v[84:87], v[136:139], v[182:185], v[84:87]
	v_mfma_f32_16x16x32_bf16 v[112:115], v[128:131], v[192:195], v[112:115]
	v_mfma_f32_16x16x32_bf16 v[80:83], v[136:139], v[192:195], v[80:83]
	v_mfma_f32_16x16x32_bf16 v[124:127], v[132:135], v[148:151], v[124:127]
	v_mfma_f32_16x16x32_bf16 v[92:95], v[140:143], v[148:151], v[92:95]
	v_mfma_f32_16x16x32_bf16 v[120:123], v[132:135], v[178:181], v[120:123]
	v_mfma_f32_16x16x32_bf16 v[88:91], v[140:143], v[178:181], v[88:91]
	v_mfma_f32_16x16x32_bf16 v[116:119], v[132:135], v[186:189], v[116:119]
	v_mfma_f32_16x16x32_bf16 v[84:87], v[140:143], v[186:189], v[84:87]
	v_mfma_f32_16x16x32_bf16 v[112:115], v[132:135], v[196:199], v[112:115]
	v_mfma_f32_16x16x32_bf16 v[80:83], v[140:143], v[196:199], v[80:83]
	s_barrier
	s_add_i32 s20, 0, 0x1c000
	s_add_i32 s21, s87, s96
	v_add_u32_e32 v164, s20, v167
	v_lshl_add_u64 v[228:229], v[212:213], 0, s[50:51]
	s_mov_b32 m0, s21
	ds_read_b128 v[200:203], v164
	ds_read_b128 v[204:207], v164 offset:1024
	ds_read_b128 v[208:211], v164 offset:2048
	ds_read_b128 v[220:223], v164 offset:3072
	global_load_lds_dwordx4 v[228:229], off
	v_lshl_add_u64 v[228:229], v[212:213], 0, s[52:53]
	s_add_i32 m0, s21, 0x2000
	s_nop 0
	global_load_lds_dwordx4 v[228:229], off
	s_barrier
	s_waitcnt lgkmcnt(0)
	s_waitcnt lgkmcnt(0)
	v_mfma_f32_16x16x32_bf16 v[108:111], v[200:203], v[144:147], v[108:111]
	v_mfma_f32_16x16x32_bf16 v[76:79], v[208:211], v[144:147], v[76:79]
	v_mfma_f32_16x16x32_bf16 v[104:107], v[200:203], v[152:155], v[104:107]
	v_mfma_f32_16x16x32_bf16 v[72:75], v[208:211], v[152:155], v[72:75]
	v_mfma_f32_16x16x32_bf16 v[100:103], v[200:203], v[182:185], v[100:103]
	v_mfma_f32_16x16x32_bf16 v[68:71], v[208:211], v[182:185], v[68:71]
	v_mfma_f32_16x16x32_bf16 v[96:99], v[200:203], v[192:195], v[96:99]
	v_mfma_f32_16x16x32_bf16 v[64:67], v[208:211], v[192:195], v[64:67]
	v_mfma_f32_16x16x32_bf16 v[108:111], v[204:207], v[148:151], v[108:111]
	v_mfma_f32_16x16x32_bf16 v[76:79], v[220:223], v[148:151], v[76:79]
	v_mfma_f32_16x16x32_bf16 v[104:107], v[204:207], v[178:181], v[104:107]
	v_mfma_f32_16x16x32_bf16 v[72:75], v[220:223], v[178:181], v[72:75]
	v_mfma_f32_16x16x32_bf16 v[100:103], v[204:207], v[186:189], v[100:103]
	v_mfma_f32_16x16x32_bf16 v[68:71], v[220:223], v[186:189], v[68:71]
	v_mfma_f32_16x16x32_bf16 v[96:99], v[204:207], v[196:199], v[96:99]
	v_mfma_f32_16x16x32_bf16 v[64:67], v[220:223], v[196:199], v[64:67]
	s_mov_b32 m0, s64
	v_lshl_add_u64 v[224:225], v[224:225], 0, s[54:55]
	s_barrier
	ds_read_b128 v[144:147], v216 offset:49152
	ds_read_b128 v[148:151], v216 offset:50176
	ds_read_b128 v[152:155], v216 offset:51200
	ds_read_b128 v[178:181], v216 offset:52224
	ds_read_b128 v[182:185], v216 offset:53248
	ds_read_b128 v[186:189], v216 offset:54272
	ds_read_b128 v[192:195], v216 offset:55296
	ds_read_b128 v[196:199], v216 offset:56320
	global_load_lds_dwordx4 v[224:225], off
	v_lshl_add_u64 v[224:225], v[226:227], 0, s[54:55]
	s_mov_b32 m0, s65
	s_nop 0
	global_load_lds_dwordx4 v[224:225], off
	s_barrier
	s_waitcnt lgkmcnt(0)
	s_waitcnt lgkmcnt(0)
	v_mfma_f32_16x16x32_bf16 v[60:63], v[128:131], v[144:147], v[60:63]
	v_mfma_f32_16x16x32_bf16 v[28:31], v[136:139], v[144:147], v[28:31]
	v_mfma_f32_16x16x32_bf16 v[56:59], v[128:131], v[152:155], v[56:59]
	v_mfma_f32_16x16x32_bf16 v[24:27], v[136:139], v[152:155], v[24:27]
	v_mfma_f32_16x16x32_bf16 v[52:55], v[128:131], v[182:185], v[52:55]
	v_mfma_f32_16x16x32_bf16 v[20:23], v[136:139], v[182:185], v[20:23]
	v_mfma_f32_16x16x32_bf16 v[48:51], v[128:131], v[192:195], v[48:51]
	v_mfma_f32_16x16x32_bf16 v[16:19], v[136:139], v[192:195], v[16:19]
	v_mfma_f32_16x16x32_bf16 v[60:63], v[132:135], v[148:151], v[60:63]
	v_mfma_f32_16x16x32_bf16 v[28:31], v[140:143], v[148:151], v[28:31]
	v_mfma_f32_16x16x32_bf16 v[56:59], v[132:135], v[178:181], v[56:59]
	v_mfma_f32_16x16x32_bf16 v[24:27], v[140:143], v[178:181], v[24:27]
	v_mfma_f32_16x16x32_bf16 v[52:55], v[132:135], v[186:189], v[52:55]
	v_mfma_f32_16x16x32_bf16 v[20:23], v[140:143], v[186:189], v[20:23]
	v_mfma_f32_16x16x32_bf16 v[48:51], v[132:135], v[196:199], v[48:51]
	v_mfma_f32_16x16x32_bf16 v[16:19], v[140:143], v[196:199], v[16:19]
	s_barrier
	s_add_i32 s20, s20, s96
	v_lshl_add_u64 v[128:129], v[212:213], 0, s[56:57]
	s_mov_b32 m0, s20
	s_nop 0
	global_load_lds_dwordx4 v[128:129], off
	v_lshl_add_u64 v[128:129], v[212:213], 0, s[58:59]
	s_add_i32 m0, s20, 0x2000
	s_nop 0
	global_load_lds_dwordx4 v[128:129], off
	s_waitcnt vmcnt(6)
	s_barrier
	v_mfma_f32_16x16x32_bf16 v[44:47], v[200:203], v[144:147], v[44:47]
	v_mfma_f32_16x16x32_bf16 v[12:15], v[208:211], v[144:147], v[12:15]
	v_mfma_f32_16x16x32_bf16 v[40:43], v[200:203], v[152:155], v[40:43]
	v_mfma_f32_16x16x32_bf16 v[8:11], v[208:211], v[152:155], v[8:11]
	v_mfma_f32_16x16x32_bf16 v[36:39], v[200:203], v[182:185], v[36:39]
	v_mfma_f32_16x16x32_bf16 v[4:7], v[208:211], v[182:185], v[4:7]
	v_mfma_f32_16x16x32_bf16 v[32:35], v[200:203], v[192:195], v[32:35]
	v_mfma_f32_16x16x32_bf16 v[0:3], v[208:211], v[192:195], v[0:3]
	v_mfma_f32_16x16x32_bf16 v[44:47], v[204:207], v[148:151], v[44:47]
	v_mfma_f32_16x16x32_bf16 v[12:15], v[220:223], v[148:151], v[12:15]
	v_mfma_f32_16x16x32_bf16 v[40:43], v[204:207], v[178:181], v[40:43]
	v_mfma_f32_16x16x32_bf16 v[8:11], v[220:223], v[178:181], v[8:11]
	v_mfma_f32_16x16x32_bf16 v[36:39], v[204:207], v[186:189], v[36:39]
	v_mfma_f32_16x16x32_bf16 v[4:7], v[220:223], v[186:189], v[4:7]
	v_mfma_f32_16x16x32_bf16 v[32:35], v[204:207], v[196:199], v[32:35]
	v_mfma_f32_16x16x32_bf16 v[0:3], v[220:223], v[196:199], v[0:3]
	s_add_i32 s86, s86, 2
	s_add_u32 s84, s84, 0x8000
	s_addc_u32 s85, s85, 0
	s_add_u32 s18, s18, 0x100
	s_addc_u32 s19, s19, 0
	s_cmp_gt_u32 s86, 29
	s_barrier
	s_cbranch_scc0 .LBB0_1313
	s_and_b32 s11, s10, 0xff
	s_lshl_b32 s10, s16, 8
	v_readlane_b32 s16, v243, 8
	s_add_i32 s10, s10, s16
	s_lshl_b32 s79, s11, 7
	s_lshl_b32 s93, s11, 8
	s_cmpk_gt_i32 s10, 0x407f
	s_cbranch_scc1 .LBB0_1392
	v_or_b32_e32 v184, s10, v157
	v_or_b32_e32 v182, 16, v184
	v_ashrrev_i32_e32 v185, 31, v184
	v_ashrrev_i32_e32 v183, 31, v182
	v_or_b32_e32 v180, 32, v184
	v_lshl_add_u64 v[128:129], v[184:185], 2, s[48:49]
	v_lshl_add_u64 v[130:131], v[182:183], 2, s[48:49]
	v_ashrrev_i32_e32 v181, 31, v180
	v_or_b32_e32 v178, 48, v184
	global_load_dword v128, v[128:129], off
	v_ashrrev_i32_e32 v179, 31, v178
	global_load_dword v140, v[130:131], off
	v_lshl_add_u64 v[130:131], v[180:181], 2, s[48:49]
	global_load_dword v139, v[130:131], off
	v_lshl_add_u64 v[130:131], v[178:179], 2, s[48:49]
	global_load_dword v138, v[130:131], off
	s_movk_i32 s11, 0x3fff
	v_cmp_lt_i32_e64 s[18:19], s11, v184
	s_movk_i32 s11, 0x4000
	v_readlane_b32 s20, v243, 11
	v_cmp_gt_i32_e64 s[16:17], s11, v184
	v_readlane_b32 s21, v243, 12
	v_add_u32_e32 v129, 0xffffc000, v184
	s_nor_b64 s[84:85], s[16:17], s[20:21]
	v_mov_b64_e32 v[136:137], 0
	v_lshrrev_b32_e32 v179, 1, v129
	s_and_saveexec_b64 s[20:21], s[84:85]
	v_and_b32_e32 v129, 0x7fffffe6, v179
	v_add_u32_e32 v129, v129, v191
	v_mov_b64_e32 v[130:131], s[62:63]
	v_mad_u64_u32 v[136:137], s[86:87], v129, s8, v[130:131]
	s_or_b64 exec, exec, s[20:21]
	s_waitcnt vmcnt(0)
	v_fmamk_f32 v128, v128, 0x3a000000, v218
	v_cmp_gt_f32_e32 vcc, s9, v128
	v_mul_f32_e32 v129, 0x4b800000, v128
	s_or_b64 s[86:87], s[18:19], s[4:5]
	v_cndmask_b32_e32 v128, v128, v129, vcc
	v_rsq_f32_e32 v128, v128
	v_or_b32_e32 v187, s79, v166
	v_mul_f32_e32 v129, 0x45800000, v128
	v_cndmask_b32_e32 v190, v128, v129, vcc
	v_cmp_ne_u64_e32 vcc, 0, v[136:137]
	s_or_b64 s[88:89], s[86:87], vcc
	s_and_saveexec_b64 s[20:21], s[88:89]
	s_cbranch_execz .LBB0_1322
	v_pk_mul_f32 v[130:131], v[126:127], v[190:191] op_sel_hi:[1,0]
	v_pk_mul_f32 v[128:129], v[124:125], v[190:191] op_sel_hi:[1,0]
	v_pk_mul_f32 v[134:135], v[110:111], v[190:191] op_sel_hi:[1,0]
	v_pk_mul_f32 v[132:133], v[108:109], v[190:191] op_sel_hi:[1,0]
	s_and_saveexec_b64 s[88:89], s[86:87]
	s_cbranch_execz .LBB0_1320
	v_mov_b64_e32 v[144:145], s[44:45]
	s_movk_i32 s11, 0x5800
	v_mad_i64_i32 v[144:145], s[86:87], v184, s11, v[144:145]
	s_lshl_b32 s38, s93, 1
	v_lshl_add_u64 v[144:145], v[144:145], 0, s[38:39]
	v_lshlrev_b32_e32 v164, 1, v166
	v_cvt_pk_bf16_f32 v142, v128, v129
	v_cvt_pk_bf16_f32 v143, v130, v131
	v_lshl_add_u64 v[144:145], v[144:145], 0, v[164:165]
	global_store_dwordx2 v[144:145], v[142:143], off
	v_cvt_pk_bf16_f32 v142, v132, v133
	v_cvt_pk_bf16_f32 v143, v134, v135
	global_store_dwordx2 v[144:145], v[142:143], off offset:256

.LBB0_1468:
	s_setprio 0
	s_waitcnt vmcnt(0)
	v_readlane_b32 s3, v243, 5
	v_readlane_b32 s66, v243, 3
	s_cmpk_gt_u32 s3, 0xff
	v_readlane_b32 s67, v243, 4
	s_cbranch_scc1 .LBB0_1470
	s_barrier
